# retention tile loop: O phase starts with the 8 MFMAs on the wave's own P half (registers) before the P-exchange barrier, partner-P MFMAs after it; first V fragments prefetched ahead of the pack
# speedup vs baseline: 1.0062x; 1.0062x over previous
; #define LAS __attribute__((address_space(3)))
; #define RT_DMA_K(kt_, bf_, i_) __builtin_amdgcn_raw_ptr_buffer_load_lds(RK, (LAS void*)(lds + RT_K0 + (bf_) * 32768 + (w + 8 * (i_)) * 1024), 16, (int)RT_KOFF, (int)((unsigned)((b * SEQ + (kt_) * 64) * DR + h * 256) * 2u + (i_) * 65536u), 0, 0)
; #define RT_DMA_V(kt_, bf_, i_) __builtin_amdgcn_raw_ptr_buffer_load_lds(RV, (LAS void*)(lds + RT_V0 + (bf_) * 32768 + (w + 8 * (i_)) * 1024), 16, (int)RT_VOFF, (int)((unsigned)((h * 256) * MTOK + b * SEQ + (kt_) * 64) * 2u + (i_) * 1048576u), 0, 0)
; #define RT_KRD(dst, s0) do { _Pragma("unroll") for (int j_ = 0; j_ < 2; ++j_) dst[j_] = *(const LAS bf16x8*)(kb + ((((2 * ((s0) + j_)) | hh) ^ x15) << 4)); } while (0)
; #define RT_KMM(src, s0) do { _Pragma("unroll") for (int j_ = 0; j_ < 2; ++j_) st = __builtin_amdgcn_mfma_f32_32x32x16_bf16(src[j_], qf[(s0) + j_], st, 0, 0, 0); } while (0)
; __device__ __forceinline__ void p2_ret(const Frame& F, ArgsP a, int layer) {
;     ...
;                 { const LAS unsigned char* kb = lds + RT_K0 + bf * 32768 + (32 * wc + kap) * 512;
;     ...
;                   bf16x8 ka[2], kd[2], kc[2];
;                   RT_KRD(ka, 0); RT_KRD(kd, 2); __builtin_amdgcn_sched_barrier(0);
;                   RT_KRD(kc, 4); RT_KMM(ka, 0); if (pre) { RT_DMA_K(kt + 1, bf ^ 1, 0); RT_DMA_V(kt + 1, bf ^ 1, 0); } __builtin_amdgcn_sched_barrier(0);
;                   RT_KRD(ka, 6); RT_KMM(kd, 2); __builtin_amdgcn_sched_barrier(0);
;                   RT_KRD(kd, 8); RT_KMM(kc, 4); if (pre) { RT_DMA_K(kt + 1, bf ^ 1, 1); RT_DMA_V(kt + 1, bf ^ 1, 1); } __builtin_amdgcn_sched_barrier(0);
;                   RT_KRD(kc, 10); RT_KMM(ka, 6); __builtin_amdgcn_sched_barrier(0);
;                   RT_KRD(ka, 12); RT_KMM(kd, 8); if (pre) { RT_DMA_K(kt + 1, bf ^ 1, 2); RT_DMA_V(kt + 1, bf ^ 1, 2); } __builtin_amdgcn_sched_barrier(0);
;                   RT_KRD(kd, 14); RT_KMM(kc, 10); __builtin_amdgcn_sched_barrier(0);
;                   RT_KMM(ka, 12); if (pre) { RT_DMA_K(kt + 1, bf ^ 1, 3); RT_DMA_V(kt + 1, bf ^ 1, 3); } __builtin_amdgcn_sched_barrier(0);
;                   RT_KMM(kd, 14); __builtin_amdgcn_sched_barrier(0);
;     ...
;                   const LAS unsigned char* vb = lds + RT_V0 + bf * 32768 + (128 * wc + kap) * 128;
.LBB0_383:
	v_mov_b32_e32 v0, v207
	s_and_b32 s6, s31, 0x8000
	v_lshlrev_b32_e32 v99, 1, v0
	v_lshrrev_b32_e32 v100, 1, v0
	v_and_b32_e32 v98, 19, v0
	v_and_b32_e32 v99, 8, v99
	v_and_b32_e32 v100, 4, v100
	v_or3_b32 v115, v99, v98, v100
	v_ashrrev_i32_e32 v116, 5, v0
	s_add_i32 s4, s6, 0
	v_or_b32_e32 v98, s80, v115
	v_or_b32_e32 v99, 2, v116
	v_lshl_add_u32 v227, v98, 9, s4
	v_bitop3_b32 v98, v115, v116, 15 bitop3:0x6c
	v_bitop3_b32 v99, v115, v99, 15 bitop3:0x6c
	v_lshl_add_u32 v98, v98, 4, v227
	v_lshl_add_u32 v102, v99, 4, v227
	ds_read_b128 v[98:101], v98
	ds_read_b128 v[190:193], v102
	v_or_b32_e32 v102, 4, v116
	v_bitop3_b32 v102, v115, v102, 15 bitop3:0x6c
	v_or_b32_e32 v103, 6, v116
	v_lshl_add_u32 v102, v102, 4, v227
	v_bitop3_b32 v103, v115, v103, 15 bitop3:0x6c
	v_lshl_add_u32 v103, v103, 4, v227
	ds_read_b128 v[194:197], v102
	ds_read_b128 v[198:201], v103
	v_and_b32_e32 v117, 31, v0
	v_add_u32_e32 v216, s23, v116
	v_lshlrev_b32_e32 v217, 12, v216
	v_bitop3_b32 v216, v216, v117, 15 bitop3:0x6c
	v_or_b32_e32 v102, 8, v116
	s_xor_b32 s4, s6, 0x8000
	v_lshl_or_b32 v228, v216, 4, v217
	v_lshrrev_b32_e32 v217, 4, v0
	v_bitop3_b32 v102, v115, v102, 15 bitop3:0x6c
	v_or_b32_e32 v103, 10, v116
	s_add_i32 s5, s22, s4
	v_add_u32_e32 v217, s90, v217
	v_lshl_add_u32 v102, v102, 4, v227
	v_bitop3_b32 v103, v115, v103, 15 bitop3:0x6c
	s_add_i32 s7, s27, 0xfffd0000
	s_mov_b32 m0, s5
	v_lshrrev_b32_e32 v216, 3, v0
	v_xor_b32_e32 v217, v217, v0
	v_lshl_add_u32 v103, v103, 4, v227
	ds_read_b128 v[202:205], v102
	ds_read_b128 v[212:215], v103
	buffer_load_dwordx4 v228, s[40:43], s7 offen lds
	v_add_lshl_u32 v216, v216, s35, 14
	v_lshlrev_b32_e32 v217, 4, v217
	s_movk_i32 s7, 0x70
	v_and_or_b32 v229, v217, s7, v216
	s_add_i32 s7, s25, s30
	s_add_i32 m0, s33, s4
	s_add_i32 s12, s7, 0x80
	s_mov_b32 s46, s42
	s_mov_b32 s47, s43
	buffer_load_dwordx4 v229, s[44:47], s12 offen lds
	s_waitcnt lgkmcnt(5)
	v_mfma_f32_32x32x16_bf16 v[98:113], v[98:101], v[118:121], 0
	s_waitcnt lgkmcnt(4)
	v_mfma_f32_32x32x16_bf16 v[98:113], v[190:193], v[122:125], v[98:113]
	v_or_b32_e32 v190, 12, v116
	v_or_b32_e32 v191, 14, v116
	v_bitop3_b32 v190, v115, v190, 15 bitop3:0x6c
	v_bitop3_b32 v191, v115, v191, 15 bitop3:0x6c
	v_lshl_add_u32 v190, v190, 4, v227
	v_lshl_add_u32 v216, v191, 4, v227
	ds_read_b128 v[190:193], v190
	ds_read_b128 v[216:219], v216
	s_waitcnt lgkmcnt(5)
	v_mfma_f32_32x32x16_bf16 v[98:113], v[194:197], v[126:129], v[98:113]
	v_or_b32_e32 v194, 16, v116
	v_or_b32_e32 v195, 18, v116
	v_bitop3_b32 v194, v115, v194, 15 bitop3:0x6c
	v_bitop3_b32 v195, v115, v195, 15 bitop3:0x6c
	s_add_i32 s4, s4, 0
	v_lshl_add_u32 v194, v194, 4, v227
	s_add_i32 m0, s5, 0x2000
	s_waitcnt lgkmcnt(4)
	v_mfma_f32_32x32x16_bf16 v[98:113], v[198:201], v[130:133], v[98:113]
	v_lshl_add_u32 v198, v195, 4, v227
	s_add_i32 s12, s27, 0xfffe0000
	s_add_i32 s4, s4, 0x10000
	ds_read_b128 v[194:197], v194
	ds_read_b128 v[198:201], v198
	buffer_load_dwordx4 v228, s[40:43], s12 offen lds
	s_add_i32 m0, s4, s24
	s_add_i32 s12, s7, 0x100080
	buffer_load_dwordx4 v229, s[44:47], s12 offen lds
	s_waitcnt lgkmcnt(5)
	v_mfma_f32_32x32x16_bf16 v[98:113], v[202:205], v[134:137], v[98:113]
	s_waitcnt lgkmcnt(4)
	v_mfma_f32_32x32x16_bf16 v[98:113], v[212:215], v[138:141], v[98:113]
	v_or_b32_e32 v202, 20, v116
	v_or_b32_e32 v203, 22, v116
	v_bitop3_b32 v202, v115, v202, 15 bitop3:0x6c
	v_bitop3_b32 v203, v115, v203, 15 bitop3:0x6c
	v_lshl_add_u32 v202, v202, 4, v227
	v_lshl_add_u32 v212, v203, 4, v227
	ds_read_b128 v[202:205], v202
	ds_read_b128 v[212:215], v212
	s_waitcnt lgkmcnt(5)
	v_mfma_f32_32x32x16_bf16 v[98:113], v[190:193], v[142:145], v[98:113]
	v_or_b32_e32 v190, 24, v116
	v_or_b32_e32 v191, 26, v116
	v_bitop3_b32 v190, v115, v190, 15 bitop3:0x6c
	v_bitop3_b32 v191, v115, v191, 15 bitop3:0x6c
	v_lshl_add_u32 v190, v190, 4, v227
	s_add_i32 m0, s5, 0x4000
	s_add_i32 s12, s27, 0xffff0000
	s_waitcnt lgkmcnt(4)
	v_mfma_f32_32x32x16_bf16 v[98:113], v[216:219], v[146:149], v[98:113]
	v_lshl_add_u32 v216, v191, 4, v227
	ds_read_b128 v[190:193], v190
	ds_read_b128 v[216:219], v216
	buffer_load_dwordx4 v228, s[40:43], s12 offen lds
	s_add_i32 m0, s4, s26
	s_add_i32 s12, s7, 0x200080
	buffer_load_dwordx4 v229, s[44:47], s12 offen lds
	s_waitcnt lgkmcnt(5)
	v_mfma_f32_32x32x16_bf16 v[98:113], v[194:197], v[150:153], v[98:113]
	s_waitcnt lgkmcnt(4)
	v_mfma_f32_32x32x16_bf16 v[98:113], v[198:201], v[154:157], v[98:113]
	s_waitcnt lgkmcnt(3)
	v_mfma_f32_32x32x16_bf16 v[98:113], v[202:205], v[158:161], v[98:113]
	v_or_b32_e32 v194, 28, v116
	v_or_b32_e32 v195, 30, v116
	v_bitop3_b32 v194, v115, v194, 15 bitop3:0x6c
	v_bitop3_b32 v195, v115, v195, 15 bitop3:0x6c
	v_lshl_add_u32 v194, v194, 4, v227
	v_lshl_add_u32 v198, v195, 4, v227
	ds_read_b128 v[194:197], v194
	ds_read_b128 v[198:201], v198
	s_waitcnt lgkmcnt(4)
	v_mfma_f32_32x32x16_bf16 v[98:113], v[212:215], v[162:165], v[98:113]
	s_add_i32 m0, s5, 0x6000
	s_add_i32 s7, s7, 0x300080
	buffer_load_dwordx4 v228, s[40:43], s27 offen lds
	s_add_i32 m0, s4, s28
	s_waitcnt lgkmcnt(3)
	v_mfma_f32_32x32x16_bf16 v[98:113], v[190:193], v[166:169], v[98:113]
	buffer_load_dwordx4 v229, s[44:47], s7 offen lds
	s_waitcnt lgkmcnt(2)
	v_mfma_f32_32x32x16_bf16 v[98:113], v[216:219], v[170:173], v[98:113]
	s_waitcnt lgkmcnt(1)
	v_mfma_f32_32x32x16_bf16 v[98:113], v[194:197], v[174:177], v[98:113]
	s_waitcnt lgkmcnt(0)
	v_mfma_f32_32x32x16_bf16 v[98:113], v[198:201], v[178:181], v[98:113]
	v_lshlrev_b32_e32 v250, 3, v115
	v_and_b32_e32 v250, 0x70, v250
	s_add_i32 s13, s64, s6
	v_lshl_add_u32 v251, v115, 7, s13
	v_lshlrev_b32_e32 v252, 4, v116
	s_lshl_b32 s14, s80, 1
	v_xad_u32 v246, v250, v252, v251
	v_add_u32_e32 v253, 32, v252
	v_xad_u32 v247, v250, v253, v251
	v_xor_b32_e32 v246, s14, v246
	v_xor_b32_e32 v247, s14, v247
	v_xor_b32_e32 v248, 64, v246
	v_xor_b32_e32 v249, 64, v247
	ds_read_b128 v[234:237], v246
	ds_read_b128 v[238:241], v247
	s_cmp_ge_u32 s91, s29
	s_mov_b64 s[4:5], -1
	s_cbranch_scc0 .LBB0_385
; __device__ __forceinline__ unsigned cvt_pk_bf16(float lo, float hi) { unsigned r; asm volatile("v_cvt_pk_bf16_f32 %0, %1, %2" : "=v"(r) : "v"(lo), "v"(hi)); return r; }
; __device__ __forceinline__ void p2_ret(const Frame& F, ArgsP a, int layer) {
;     ...
;                   } else { const int lim = wr * 32 + l31 + (2 * qi - kt) * 64 - 32 * wc - 8 * hh;
; #pragma unroll
;                       for (int i = 0; i < 8; ++i) { const int r0 = 2 * i, r1 = 2 * i + 1, o0 = 16 * (r0 >> 3) + (r0 & 7), o1 = 16 * (r1 >> 3) + (r1 & 7);
;                           pk[i] = cvt_pk_bf16((o0 <= lim) ? st[r0] : 0.f, (o1 <= lim) ? st[r1] : 0.f); } }
	v_lshlrev_b32_e32 v190, 3, v116
	v_sub_u32_e32 v117, v117, v190
	v_add_u32_e32 v117, s97, v117
	v_cmp_lt_i32_e32 vcc, -1, v117
	s_mov_b64 s[4:5], 0
	s_nop 3
	v_cndmask_b32_e32 v190, 0, v98, vcc
	v_cmp_lt_i32_e32 vcc, 0, v117
	s_nop 1
	v_cndmask_b32_e32 v191, 0, v99, vcc
	v_cmp_lt_i32_e32 vcc, 1, v117
	v_cvt_pk_bf16_f32 v190, v190, v191
	s_nop 1
	v_cndmask_b32_e32 v191, 0, v100, vcc
	v_cmp_lt_i32_e32 vcc, 2, v117
	s_nop 1
	v_cndmask_b32_e32 v192, 0, v101, vcc
	v_cmp_lt_i32_e32 vcc, 3, v117
	v_cvt_pk_bf16_f32 v191, v191, v192
	s_nop 1
	v_cndmask_b32_e32 v192, 0, v102, vcc
	v_cmp_lt_i32_e32 vcc, 4, v117
	s_nop 1
	v_cndmask_b32_e32 v193, 0, v103, vcc
	v_cmp_lt_i32_e32 vcc, 5, v117
	v_cvt_pk_bf16_f32 v192, v192, v193
	s_nop 1
	v_cndmask_b32_e32 v193, 0, v104, vcc
	v_cmp_lt_i32_e32 vcc, 6, v117
	s_nop 1
	v_cndmask_b32_e32 v194, 0, v105, vcc
	v_cmp_lt_i32_e32 vcc, 15, v117
	v_cvt_pk_bf16_f32 v193, v193, v194
	s_nop 1
	v_cndmask_b32_e32 v194, 0, v106, vcc
	v_cmp_lt_i32_e32 vcc, 16, v117
	s_nop 1
	v_cndmask_b32_e32 v195, 0, v107, vcc
	v_cmp_lt_i32_e32 vcc, 17, v117
	v_cvt_pk_bf16_f32 v194, v194, v195
	s_nop 1
	v_cndmask_b32_e32 v195, 0, v108, vcc
	v_cmp_lt_i32_e32 vcc, 18, v117
	s_nop 1
	v_cndmask_b32_e32 v196, 0, v109, vcc
	v_cmp_lt_i32_e32 vcc, 19, v117
	v_cvt_pk_bf16_f32 v195, v195, v196
	s_nop 1
	v_cndmask_b32_e32 v196, 0, v110, vcc
	v_cmp_lt_i32_e32 vcc, 20, v117
	s_nop 1
	v_cndmask_b32_e32 v197, 0, v111, vcc
	v_cmp_lt_i32_e32 vcc, 21, v117
	v_cvt_pk_bf16_f32 v196, v196, v197
	s_nop 1
	v_cndmask_b32_e32 v197, 0, v112, vcc
	v_cmp_lt_i32_e32 vcc, 22, v117
	s_nop 1
	v_cndmask_b32_e32 v117, 0, v113, vcc
	v_cvt_pk_bf16_f32 v197, v197, v117

; #define LAS __attribute__((address_space(3)))
; #define RT_BAR() do { asm volatile("s_waitcnt lgkmcnt(0)" ::: "memory"); __builtin_amdgcn_s_barrier(); asm volatile("" ::: "memory"); } while (0)
; #define RT_VRD(dst, g) do { _Pragma("unroll") for (int j_ = 0; j_ < 2; ++j_) { const int jj_ = 2 * ((g) & 1) + j_; dst[j_] = *(const LAS bf16x8*)(vb + ((g) >> 1) * 4096 + (((4 * (jj_ >> 1) + 2 * (jj_ & 1) + hh) << 4) ^ m4)); } } while (0)
; #define RT_VMM(src, g) do { _Pragma("unroll") for (int j_ = 0; j_ < 2; ++j_) { const int jj_ = 2 * ((g) & 1) + j_; oacc[(g) >> 1] = __builtin_amdgcn_mfma_f32_32x32x16_bf16(src[j_], pf[jj_ >> 1][jj_ & 1], oacc[(g) >> 1], 0, 0, 0); } } while (0)
; __device__ __forceinline__ void p2_ret(const Frame& F, ArgsP a, int layer) {
;     ...
;                   LAS unsigned char* pw = lds + RT_P + ((wr * 2 + wc) * 2) * 1024 + lane * 16;
;                   *(LAS u32x4*)pw = (u32x4){pk[0], pk[1], pk[2], pk[3]}; *(LAS u32x4*)(pw + 1024) = (u32x4){pk[4], pk[5], pk[6], pk[7]}; }
;                 RT_BAR();
;                 { bf16x8 pf[2][2];
; #pragma unroll
;                   for (int kb2 = 0; kb2 < 2; ++kb2)
; #pragma unroll
;                       for (int s = 0; s < 2; ++s) pf[kb2][s] = *(const LAS bf16x8*)(lds + RT_P + ((wr * 2 + kb2) * 2 + s) * 1024 + lane * 16);
;                   const LAS unsigned char* vb = lds + RT_V0 + bf * 32768 + (128 * wc + kap) * 128;
;     ...
;                   bf16x8 va[2], vc[2];
;                   RT_VRD(va, 0); __builtin_amdgcn_sched_barrier(0);
;                   RT_VRD(vc, 1); RT_VMM(va, 0); __builtin_amdgcn_sched_barrier(0);
;                   RT_VRD(va, 2); RT_VMM(vc, 1); __builtin_amdgcn_sched_barrier(0);
;                   RT_VRD(vc, 3); RT_VMM(va, 2); __builtin_amdgcn_sched_barrier(0);
;                   RT_VRD(va, 4); RT_VMM(vc, 3); __builtin_amdgcn_sched_barrier(0);
;                   RT_VRD(vc, 5); RT_VMM(va, 4); __builtin_amdgcn_sched_barrier(0);
;                   RT_VRD(va, 6); RT_VMM(vc, 5); __builtin_amdgcn_sched_barrier(0);
;                   RT_VRD(vc, 7); RT_VMM(va, 6); __builtin_amdgcn_sched_barrier(0);
;                   RT_VMM(vc, 7); __builtin_amdgcn_sched_barrier(0);
.LBB0_387:
	s_nop 6
	v_lshlrev_b32_e32 v98, 4, v0
	v_add_u32_e32 v99, s83, v98
	ds_write_b128 v99, v[190:193]
	ds_write_b128 v99, v[194:197] offset:1024
	s_lshl_b32 s12, s80, 6
	s_sub_i32 s12, 0x800, s12
	s_add_i32 s12, s12, s82
	v_add_u32_e32 v250, s12, v98
	ds_read_b128 v[242:245], v246 offset:4096
	ds_read_b128 v[106:109], v247 offset:4096
	s_waitcnt lgkmcnt(5)
	v_mfma_f32_32x32x16_bf16 v[82:97], v[234:237], v[190:193], v[82:97]
	s_waitcnt lgkmcnt(4)
	v_mfma_f32_32x32x16_bf16 v[82:97], v[238:241], v[194:197], v[82:97]
	ds_read_b128 v[234:237], v246 offset:8192
	ds_read_b128 v[238:241], v247 offset:8192
	s_waitcnt lgkmcnt(3)
	v_mfma_f32_32x32x16_bf16 v[66:81], v[242:245], v[190:193], v[66:81]
	s_waitcnt lgkmcnt(2)
	v_mfma_f32_32x32x16_bf16 v[66:81], v[106:109], v[194:197], v[66:81]
	ds_read_b128 v[242:245], v246 offset:12288
	ds_read_b128 v[106:109], v247 offset:12288
	s_waitcnt lgkmcnt(3)
	v_mfma_f32_32x32x16_bf16 v[50:65], v[234:237], v[190:193], v[50:65]
	s_waitcnt lgkmcnt(2)
	v_mfma_f32_32x32x16_bf16 v[50:65], v[238:241], v[194:197], v[50:65]
	ds_read_b128 v[234:237], v248
	ds_read_b128 v[238:241], v249
	s_barrier
	ds_read_b128 v[98:101], v250
	ds_read_b128 v[102:105], v250 offset:1024
	s_waitcnt lgkmcnt(5)
	v_mfma_f32_32x32x16_bf16 v[34:49], v[242:245], v[190:193], v[34:49]
	s_waitcnt lgkmcnt(4)
	v_mfma_f32_32x32x16_bf16 v[34:49], v[106:109], v[194:197], v[34:49]
	ds_read_b128 v[242:245], v248 offset:4096
	ds_read_b128 v[106:109], v249 offset:4096
	s_waitcnt lgkmcnt(2)
	v_mfma_f32_32x32x16_bf16 v[82:97], v[234:237], v[98:101], v[82:97]
	v_mfma_f32_32x32x16_bf16 v[82:97], v[238:241], v[102:105], v[82:97]
	ds_read_b128 v[234:237], v248 offset:8192
	ds_read_b128 v[238:241], v249 offset:8192
	s_waitcnt lgkmcnt(3)
	v_mfma_f32_32x32x16_bf16 v[66:81], v[242:245], v[98:101], v[66:81]
	s_waitcnt lgkmcnt(2)
	v_mfma_f32_32x32x16_bf16 v[66:81], v[106:109], v[102:105], v[66:81]
	ds_read_b128 v[242:245], v248 offset:12288
	ds_read_b128 v[106:109], v249 offset:12288
	s_waitcnt lgkmcnt(3)
	v_mfma_f32_32x32x16_bf16 v[50:65], v[234:237], v[98:101], v[50:65]
	s_waitcnt lgkmcnt(2)
	v_mfma_f32_32x32x16_bf16 v[50:65], v[238:241], v[102:105], v[50:65]
	s_waitcnt lgkmcnt(1)
	v_mfma_f32_32x32x16_bf16 v[34:49], v[242:245], v[98:101], v[34:49]
	s_waitcnt lgkmcnt(0)
	v_mfma_f32_32x32x16_bf16 v[34:49], v[106:109], v[102:105], v[34:49]
	s_waitcnt vmcnt(0)
	s_and_b64 vcc, exec, s[38:39]
	s_cbranch_vccnz .LBB0_357
	s_ashr_i32 s14, s36, 1
	s_cmpk_lt_i32 s14, 0x400
	s_cselect_b64 s[4:5], -1, 0
	s_mov_b64 s[70:71], 0
	s_and_b64 vcc, exec, s[4:5]
	s_cbranch_vccnz .LBB0_394
	s_mov_b64 s[46:47], -1
	s_cmpk_gt_u32 s14, 0x13ff
	s_mov_b64 s[6:7], -1
	s_cbranch_scc0 .LBB0_391
	s_add_i32 s12, s14, 0xffffec00
	s_mov_b64 s[6:7], 0
